# S5 pass2 GELU epilogue: tanh via hardware exp2 and rcp (1 - 2/(1+e^2x)) in f32 instead of the branchy library tanhf; output is bf16
# baseline (speedup 1.0000x reference)
.LBB0_1811:
	s_or_b64 exec, exec, s[0:1]
	s_waitcnt vmcnt(0) lgkmcnt(0)
	v_mov_b32_e32 v158, 0x5040100
	v_mov_b32_e32 v159, 0x7060302
	v_perm_b32 v32, v142, v140, v158
	v_perm_b32 v33, v142, v140, v159
	v_perm_b32 v34, v143, v141, v158
	v_perm_b32 v35, v143, v141, v159
	v_perm_b32 v28, v146, v144, v158
	v_perm_b32 v29, v146, v144, v159
	v_perm_b32 v30, v147, v145, v158
	v_perm_b32 v31, v147, v145, v159
	v_perm_b32 v24, v150, v148, v158
	v_perm_b32 v25, v150, v148, v159
	v_perm_b32 v26, v151, v149, v158
	v_perm_b32 v27, v151, v149, v159
	v_perm_b32 v20, v154, v152, v158
	v_perm_b32 v21, v154, v152, v159
	v_perm_b32 v22, v155, v153, v158
	v_perm_b32 v23, v155, v153, v159
	v_mfma_f32_16x16x32_bf16 v[94:97], v[16:19], v[40:43], 0
	v_mul_u32_u24_e32 v86, 0x210, v93
	v_lshlrev_b32_e32 v87, 2, v92
	v_lshlrev_b32_e32 v86, 2, v86
	v_mfma_f32_16x16x32_bf16 v[98:101], v[16:19], v[36:39], 0
	v_add3_u32 v88, v81, v87, v86
	v_add_u32_e32 v89, 0x400, v88
	v_mul_u32_u24_e32 v103, 0x110, v92
	s_nop 4
	ds_write2_b32 v88, v94, v98 offset1:16
	ds_write2_b32 v88, v95, v99 offset0:132 offset1:148
	ds_write2_b32 v89, v96, v100 offset0:8 offset1:24
	ds_write2_b32 v89, v97, v101 offset0:140 offset1:156
	v_mfma_f32_16x16x32_bf16 v[92:95], v[16:19], v[48:51], 0
	v_lshl_add_u32 v87, v91, 2, v81
	v_add3_u32 v81, v81, v128, v103
	v_pk_add_f32 v[0:1], v[0:1], 0 op_sel_hi:[1,0]
	v_mfma_f32_16x16x32_bf16 v[96:99], v[16:19], v[44:47], 0
	s_nop 7
	ds_write2_b32 v88, v92, v96 offset0:32 offset1:48
	ds_write2_b32 v88, v93, v97 offset0:164 offset1:180
	ds_write2_b32 v89, v94, v98 offset0:40 offset1:56
	ds_write2_b32 v89, v95, v99 offset0:172 offset1:188
	v_mfma_f32_16x16x32_bf16 v[92:95], v[16:19], v[56:59], 0
	v_readlane_b32 s68, v251, 41
	v_readlane_b32 s76, v251, 49
	v_readlane_b32 s77, v251, 50
	v_mfma_f32_16x16x32_bf16 v[96:99], v[16:19], v[52:55], 0
	s_nop 7
	ds_write2_b32 v88, v92, v96 offset0:64 offset1:80
	ds_write2_b32 v88, v93, v97 offset0:196 offset1:212
	ds_write2_b32 v89, v94, v98 offset0:72 offset1:88
	ds_write2_b32 v89, v95, v99 offset0:204 offset1:220
	v_mfma_f32_16x16x32_bf16 v[92:95], v[16:19], v[64:67], 0
	s_mov_b32 s10, 0x3f200000
	v_readlane_b32 s69, v251, 42
	v_readlane_b32 s70, v251, 43
	v_mfma_f32_16x16x32_bf16 v[16:19], v[16:19], v[60:63], 0
	s_nop 7
	ds_write2_b32 v88, v92, v16 offset0:96 offset1:112
	ds_write2_b32 v88, v93, v17 offset0:228 offset1:244
	ds_write2_b32 v89, v94, v18 offset0:104 offset1:120
	ds_write2_b32 v89, v95, v19 offset0:236 offset1:252
	v_lshlrev_b32_e32 v16, 1, v91
	v_add_u32_e32 v91, 0xf0, v87
	s_waitcnt vmcnt(0) lgkmcnt(0)
	v_sub_u32_e32 v86, v87, v16
	ds_read2st64_b32 v[16:17], v91 offset0:30 offset1:31
	v_add_u32_e32 v140, 0xe0, v87
	ds_read2st64_b32 v[142:143], v140 offset0:28 offset1:29
	v_add_u32_e32 v141, 0xd0, v87
	ds_read2st64_b32 v[144:145], v141 offset0:26 offset1:27
	v_add_u32_e32 v146, 0xc0, v87
	ds_read2st64_b32 v[148:149], v146 offset0:24 offset1:25
	v_add_u32_e32 v147, 0xb0, v87
	ds_read2st64_b32 v[150:151], v147 offset0:22 offset1:23
	v_add_u32_e32 v152, 0xa0, v87
	ds_read2st64_b32 v[154:155], v152 offset0:20 offset1:21
	v_add_u32_e32 v153, 0x90, v87
	ds_read2st64_b32 v[156:157], v153 offset0:18 offset1:19
	v_add_u32_e32 v158, 0x80, v87
	ds_read2st64_b32 v[160:161], v158 offset0:16 offset1:17
	v_add_u32_e32 v159, 0x70, v87
	ds_read2st64_b32 v[162:163], v159 offset0:14 offset1:15
	v_add_u32_e32 v164, 0x60, v87
	ds_read2st64_b32 v[166:167], v164 offset0:12 offset1:13
	v_add_u32_e32 v165, 0x50, v87
	ds_read2st64_b32 v[168:169], v165 offset0:10 offset1:11
	v_add_u32_e32 v170, 64, v87
	ds_read2st64_b32 v[172:173], v170 offset0:8 offset1:9
	v_add_u32_e32 v171, 48, v87
	ds_read2st64_b32 v[174:175], v171 offset0:6 offset1:7
	v_add_u32_e32 v176, 32, v87
	ds_read2st64_b32 v[178:179], v176 offset0:4 offset1:5
	ds_read2_b32 v[180:181], v87 offset0:132 offset1:196
	ds_read2st64_b32 v[182:183], v87 offset1:1
	v_mov_b32_e32 v186, v84
	v_mov_b32_e32 v187, v85
	v_mfma_f32_16x16x32_bf16 v[108:111], v[72:75], v[36:39], 0
	v_readlane_b32 s71, v251, 44
	s_waitcnt lgkmcnt(0)
	v_pk_fma_f32 v[184:185], v[82:83], v[186:187], v[16:17] op_sel:[1,1,0] op_sel_hi:[1,0,1] neg_lo:[1,0,0]
	v_pk_fma_f32 v[188:189], v[82:83], v[186:187], v[184:185] op_sel_hi:[0,1,1]
	v_cvt_pk_bf16_f32 v190, v188, v189
	v_and_b32_e32 v191, 63, v207
	v_lshl_add_u32 v191, v191, 1, v86
	ds_write_b32 v191, v190 offset:12528
	v_add_u32_e32 v84, 0xe0, v87
	v_readlane_b32 s72, v251, 45
	v_readlane_b32 s73, v251, 46
	v_pk_fma_f32 v[184:185], v[82:83], v[188:189], v[142:143] op_sel:[1,1,0] op_sel_hi:[1,0,1] neg_lo:[1,0,0]
	v_pk_fma_f32 v[186:187], v[82:83], v[188:189], v[184:185] op_sel_hi:[0,1,1]
	v_cvt_pk_bf16_f32 v190, v186, v187
	ds_write_b32 v191, v190 offset:12256
	v_add_u32_e32 v85, 0xd0, v87
	v_readlane_b32 s74, v251, 47
	v_readlane_b32 s75, v251, 48
	v_pk_fma_f32 v[184:185], v[82:83], v[186:187], v[144:145] op_sel:[1,1,0] op_sel_hi:[1,0,1] neg_lo:[1,0,0]
	v_pk_fma_f32 v[188:189], v[82:83], v[186:187], v[184:185] op_sel_hi:[0,1,1]
	v_cvt_pk_bf16_f32 v190, v188, v189
	ds_write_b32 v191, v190 offset:11984
	v_add_u32_e32 v92, 0xc0, v87
	v_readlane_b32 s78, v251, 51
	v_readlane_b32 s79, v251, 52
	v_pk_fma_f32 v[184:185], v[82:83], v[188:189], v[148:149] op_sel:[1,1,0] op_sel_hi:[1,0,1] neg_lo:[1,0,0]
	v_pk_fma_f32 v[186:187], v[82:83], v[188:189], v[184:185] op_sel_hi:[0,1,1]
	v_cvt_pk_bf16_f32 v190, v186, v187
	ds_write_b32 v191, v190 offset:11712
	v_add_u32_e32 v93, 0xb0, v87
	v_readlane_b32 s80, v251, 53
	v_readlane_b32 s81, v251, 54
	v_pk_fma_f32 v[184:185], v[82:83], v[186:187], v[150:151] op_sel:[1,1,0] op_sel_hi:[1,0,1] neg_lo:[1,0,0]
	v_pk_fma_f32 v[188:189], v[82:83], v[186:187], v[184:185] op_sel_hi:[0,1,1]
	v_cvt_pk_bf16_f32 v190, v188, v189
	ds_write_b32 v191, v190 offset:11440
	v_add_u32_e32 v94, 0xa0, v87
	v_readlane_b32 s82, v251, 55
	v_readlane_b32 s83, v251, 56
	v_pk_fma_f32 v[184:185], v[82:83], v[188:189], v[154:155] op_sel:[1,1,0] op_sel_hi:[1,0,1] neg_lo:[1,0,0]
	v_pk_fma_f32 v[186:187], v[82:83], v[188:189], v[184:185] op_sel_hi:[0,1,1]
	v_cvt_pk_bf16_f32 v190, v186, v187
	ds_write_b32 v191, v190 offset:11168
	v_add_u32_e32 v95, 0x90, v87
	v_pk_fma_f32 v[184:185], v[82:83], v[186:187], v[156:157] op_sel:[1,1,0] op_sel_hi:[1,0,1] neg_lo:[1,0,0]
	v_pk_fma_f32 v[188:189], v[82:83], v[186:187], v[184:185] op_sel_hi:[0,1,1]
	v_cvt_pk_bf16_f32 v190, v188, v189
	ds_write_b32 v191, v190 offset:10896
	v_add_u32_e32 v96, 0x80, v87
	v_pk_fma_f32 v[184:185], v[82:83], v[188:189], v[160:161] op_sel:[1,1,0] op_sel_hi:[1,0,1] neg_lo:[1,0,0]
	v_pk_fma_f32 v[186:187], v[82:83], v[188:189], v[184:185] op_sel_hi:[0,1,1]
	v_cvt_pk_bf16_f32 v190, v186, v187
	ds_write_b32 v191, v190 offset:10624
	v_add_u32_e32 v97, 0x70, v87
	v_pk_fma_f32 v[184:185], v[82:83], v[186:187], v[162:163] op_sel:[1,1,0] op_sel_hi:[1,0,1] neg_lo:[1,0,0]
	v_pk_fma_f32 v[188:189], v[82:83], v[186:187], v[184:185] op_sel_hi:[0,1,1]
	v_cvt_pk_bf16_f32 v190, v188, v189
	ds_write_b32 v191, v190 offset:10352
	v_add_u32_e32 v98, 0x60, v87
	v_pk_fma_f32 v[184:185], v[82:83], v[188:189], v[166:167] op_sel:[1,1,0] op_sel_hi:[1,0,1] neg_lo:[1,0,0]
	v_pk_fma_f32 v[186:187], v[82:83], v[188:189], v[184:185] op_sel_hi:[0,1,1]
	v_cvt_pk_bf16_f32 v190, v186, v187
	ds_write_b32 v191, v190 offset:10080
	v_add_u32_e32 v99, 0x50, v87
	v_pk_fma_f32 v[184:185], v[82:83], v[186:187], v[168:169] op_sel:[1,1,0] op_sel_hi:[1,0,1] neg_lo:[1,0,0]
	v_pk_fma_f32 v[188:189], v[82:83], v[186:187], v[184:185] op_sel_hi:[0,1,1]
	v_cvt_pk_bf16_f32 v190, v188, v189
	ds_write_b32 v191, v190 offset:9808
	v_add_u32_e32 v100, 64, v87
	v_pk_fma_f32 v[184:185], v[82:83], v[188:189], v[172:173] op_sel:[1,1,0] op_sel_hi:[1,0,1] neg_lo:[1,0,0]
	v_pk_fma_f32 v[186:187], v[82:83], v[188:189], v[184:185] op_sel_hi:[0,1,1]
	v_cvt_pk_bf16_f32 v190, v186, v187
	ds_write_b32 v191, v190 offset:9536
	v_add_u32_e32 v101, 48, v87
	v_pk_fma_f32 v[184:185], v[82:83], v[186:187], v[174:175] op_sel:[1,1,0] op_sel_hi:[1,0,1] neg_lo:[1,0,0]
	v_pk_fma_f32 v[188:189], v[82:83], v[186:187], v[184:185] op_sel_hi:[0,1,1]
	v_cvt_pk_bf16_f32 v190, v188, v189
	ds_write_b32 v191, v190 offset:9264
	v_add_u32_e32 v102, 32, v87
	v_pk_fma_f32 v[184:185], v[82:83], v[188:189], v[178:179] op_sel:[1,1,0] op_sel_hi:[1,0,1] neg_lo:[1,0,0]
	v_pk_fma_f32 v[186:187], v[82:83], v[188:189], v[184:185] op_sel_hi:[0,1,1]
	v_cvt_pk_bf16_f32 v190, v186, v187
	ds_write_b32 v191, v190 offset:8992
	v_pk_fma_f32 v[184:185], v[82:83], v[186:187], v[180:181] op_sel:[1,1,0] op_sel_hi:[1,0,1] neg_lo:[1,0,0]
	v_pk_fma_f32 v[188:189], v[82:83], v[186:187], v[184:185] op_sel_hi:[0,1,1]
	v_cvt_pk_bf16_f32 v190, v188, v189
	ds_write_b32 v191, v190 offset:8720
	v_pk_fma_f32 v[184:185], v[82:83], v[188:189], v[182:183] op_sel:[1,1,0] op_sel_hi:[1,0,1] neg_lo:[1,0,0]
	v_pk_fma_f32 v[186:187], v[82:83], v[188:189], v[184:185] op_sel_hi:[0,1,1]
	v_mov_b32_e32 v112, v186
	v_mov_b32_e32 v113, v187
	v_cvt_pk_bf16_f32 v190, v186, v187
	ds_write_b32 v191, v190 offset:8448
	s_waitcnt vmcnt(0) lgkmcnt(0)
	ds_read_b128 v[16:19], v81 offset:8448
	ds_read_b128 v[104:107], v81 offset:8512
	s_waitcnt lgkmcnt(1)
	v_mfma_f32_16x16x32_bf16 v[16:19], v[16:19], v[32:35], 0
	s_waitcnt lgkmcnt(0)
	v_mfma_f32_16x16x32_bf16 v[16:19], v[104:107], v[28:31], v[16:19]
	ds_read_b128 v[104:107], v81 offset:8576
	s_waitcnt lgkmcnt(0)
	v_mfma_f32_16x16x32_bf16 v[16:19], v[104:107], v[24:27], v[16:19]
	ds_read_b128 v[104:107], v81 offset:8640
	s_waitcnt lgkmcnt(0)
	v_mfma_f32_16x16x32_bf16 v[16:19], v[104:107], v[20:23], v[16:19]
	v_mfma_f32_16x16x32_bf16 v[104:107], v[72:75], v[40:43], 0
	s_nop 7
	ds_write2_b32 v88, v104, v108 offset1:16
	ds_write2_b32 v88, v105, v109 offset0:132 offset1:148
	ds_write2_b32 v89, v106, v110 offset0:8 offset1:24
	ds_write2_b32 v89, v107, v111 offset0:140 offset1:156
	v_mfma_f32_16x16x32_bf16 v[104:107], v[72:75], v[48:51], 0
	v_mfma_f32_16x16x32_bf16 v[108:111], v[72:75], v[44:47], 0
	s_nop 7
	ds_write2_b32 v88, v104, v108 offset0:32 offset1:48
	ds_write2_b32 v88, v105, v109 offset0:164 offset1:180
	ds_write2_b32 v89, v106, v110 offset0:40 offset1:56
	ds_write2_b32 v89, v107, v111 offset0:172 offset1:188
	v_mfma_f32_16x16x32_bf16 v[104:107], v[72:75], v[56:59], 0
	v_mfma_f32_16x16x32_bf16 v[108:111], v[72:75], v[52:55], 0
	s_nop 7
	ds_write2_b32 v88, v104, v108 offset0:64 offset1:80
	ds_write2_b32 v88, v105, v109 offset0:196 offset1:212
	ds_write2_b32 v89, v106, v110 offset0:72 offset1:88
	ds_write2_b32 v89, v107, v111 offset0:204 offset1:220
	v_mfma_f32_16x16x32_bf16 v[104:107], v[72:75], v[64:67], 0
	v_mfma_f32_16x16x32_bf16 v[72:75], v[72:75], v[60:63], 0
	s_nop 7
	ds_write2_b32 v88, v104, v72 offset0:96 offset1:112
	ds_write2_b32 v88, v105, v73 offset0:228 offset1:244
	ds_write2_b32 v89, v106, v74 offset0:104 offset1:120
	ds_write2_b32 v89, v107, v75 offset0:236 offset1:252
	s_waitcnt vmcnt(0) lgkmcnt(0)
	ds_read2st64_b32 v[72:73], v91 offset0:30 offset1:31
	ds_read2st64_b32 v[140:141], v84 offset0:28 offset1:29
	ds_read2st64_b32 v[142:143], v85 offset0:26 offset1:27
	ds_read2st64_b32 v[144:145], v92 offset0:24 offset1:25
	ds_read2st64_b32 v[146:147], v93 offset0:22 offset1:23
	ds_read2st64_b32 v[148:149], v94 offset0:20 offset1:21
	ds_read2st64_b32 v[150:151], v95 offset0:18 offset1:19
	ds_read2st64_b32 v[152:153], v96 offset0:16 offset1:17
	ds_read2st64_b32 v[154:155], v97 offset0:14 offset1:15
	ds_read2st64_b32 v[156:157], v98 offset0:12 offset1:13
	ds_read2st64_b32 v[158:159], v99 offset0:10 offset1:11
	ds_read2st64_b32 v[160:161], v100 offset0:8 offset1:9
	ds_read2st64_b32 v[162:163], v101 offset0:6 offset1:7
	ds_read2st64_b32 v[164:165], v102 offset0:4 offset1:5
	ds_read2_b32 v[166:167], v87 offset0:132 offset1:196
	ds_read2st64_b32 v[168:169], v87 offset1:1
	v_mov_b32_e32 v186, v112
	v_mov_b32_e32 v187, v113
	v_mfma_f32_16x16x32_bf16 v[108:111], v[76:79], v[36:39], 0
	s_waitcnt lgkmcnt(0)
	v_pk_fma_f32 v[184:185], v[82:83], v[186:187], v[72:73] op_sel:[1,1,0] op_sel_hi:[1,0,1] neg_lo:[1,0,0]
	v_pk_fma_f32 v[188:189], v[82:83], v[186:187], v[184:185] op_sel_hi:[0,1,1]
	v_cvt_pk_bf16_f32 v190, v188, v189
	v_and_b32_e32 v191, 63, v207
	v_lshl_add_u32 v191, v191, 1, v86
	ds_write_b32 v191, v190 offset:12528
	v_mfma_f32_16x16x32_bf16 v[36:39], v[68:71], v[36:39], 0
	v_pk_fma_f32 v[184:185], v[82:83], v[188:189], v[140:141] op_sel:[1,1,0] op_sel_hi:[1,0,1] neg_lo:[1,0,0]
	v_pk_fma_f32 v[186:187], v[82:83], v[188:189], v[184:185] op_sel_hi:[0,1,1]
	v_cvt_pk_bf16_f32 v190, v186, v187
	ds_write_b32 v191, v190 offset:12256
	v_pk_fma_f32 v[184:185], v[82:83], v[186:187], v[142:143] op_sel:[1,1,0] op_sel_hi:[1,0,1] neg_lo:[1,0,0]
	v_pk_fma_f32 v[188:189], v[82:83], v[186:187], v[184:185] op_sel_hi:[0,1,1]
	v_cvt_pk_bf16_f32 v190, v188, v189
	ds_write_b32 v191, v190 offset:11984
	v_pk_fma_f32 v[184:185], v[82:83], v[188:189], v[144:145] op_sel:[1,1,0] op_sel_hi:[1,0,1] neg_lo:[1,0,0]
	v_pk_fma_f32 v[186:187], v[82:83], v[188:189], v[184:185] op_sel_hi:[0,1,1]
	v_cvt_pk_bf16_f32 v190, v186, v187
	ds_write_b32 v191, v190 offset:11712
	v_pk_fma_f32 v[184:185], v[82:83], v[186:187], v[146:147] op_sel:[1,1,0] op_sel_hi:[1,0,1] neg_lo:[1,0,0]
	v_pk_fma_f32 v[188:189], v[82:83], v[186:187], v[184:185] op_sel_hi:[0,1,1]
	v_cvt_pk_bf16_f32 v190, v188, v189
	ds_write_b32 v191, v190 offset:11440
	v_pk_fma_f32 v[184:185], v[82:83], v[188:189], v[148:149] op_sel:[1,1,0] op_sel_hi:[1,0,1] neg_lo:[1,0,0]
	v_pk_fma_f32 v[186:187], v[82:83], v[188:189], v[184:185] op_sel_hi:[0,1,1]
	v_cvt_pk_bf16_f32 v190, v186, v187
	ds_write_b32 v191, v190 offset:11168
	v_pk_fma_f32 v[184:185], v[82:83], v[186:187], v[150:151] op_sel:[1,1,0] op_sel_hi:[1,0,1] neg_lo:[1,0,0]
	v_pk_fma_f32 v[188:189], v[82:83], v[186:187], v[184:185] op_sel_hi:[0,1,1]
	v_cvt_pk_bf16_f32 v190, v188, v189
	ds_write_b32 v191, v190 offset:10896
	v_pk_fma_f32 v[184:185], v[82:83], v[188:189], v[152:153] op_sel:[1,1,0] op_sel_hi:[1,0,1] neg_lo:[1,0,0]
	v_pk_fma_f32 v[186:187], v[82:83], v[188:189], v[184:185] op_sel_hi:[0,1,1]
	v_cvt_pk_bf16_f32 v190, v186, v187
	ds_write_b32 v191, v190 offset:10624
	v_pk_fma_f32 v[184:185], v[82:83], v[186:187], v[154:155] op_sel:[1,1,0] op_sel_hi:[1,0,1] neg_lo:[1,0,0]
	v_pk_fma_f32 v[188:189], v[82:83], v[186:187], v[184:185] op_sel_hi:[0,1,1]
	v_cvt_pk_bf16_f32 v190, v188, v189
	ds_write_b32 v191, v190 offset:10352
	v_pk_fma_f32 v[184:185], v[82:83], v[188:189], v[156:157] op_sel:[1,1,0] op_sel_hi:[1,0,1] neg_lo:[1,0,0]
	v_pk_fma_f32 v[186:187], v[82:83], v[188:189], v[184:185] op_sel_hi:[0,1,1]
	v_cvt_pk_bf16_f32 v190, v186, v187
	ds_write_b32 v191, v190 offset:10080
	v_pk_fma_f32 v[184:185], v[82:83], v[186:187], v[158:159] op_sel:[1,1,0] op_sel_hi:[1,0,1] neg_lo:[1,0,0]
	v_pk_fma_f32 v[188:189], v[82:83], v[186:187], v[184:185] op_sel_hi:[0,1,1]
	v_cvt_pk_bf16_f32 v190, v188, v189
	ds_write_b32 v191, v190 offset:9808
	v_pk_fma_f32 v[184:185], v[82:83], v[188:189], v[160:161] op_sel:[1,1,0] op_sel_hi:[1,0,1] neg_lo:[1,0,0]
	v_pk_fma_f32 v[186:187], v[82:83], v[188:189], v[184:185] op_sel_hi:[0,1,1]
	v_cvt_pk_bf16_f32 v190, v186, v187
	ds_write_b32 v191, v190 offset:9536
	v_pk_fma_f32 v[184:185], v[82:83], v[186:187], v[162:163] op_sel:[1,1,0] op_sel_hi:[1,0,1] neg_lo:[1,0,0]
	v_pk_fma_f32 v[188:189], v[82:83], v[186:187], v[184:185] op_sel_hi:[0,1,1]
	v_cvt_pk_bf16_f32 v190, v188, v189
	ds_write_b32 v191, v190 offset:9264
	v_pk_fma_f32 v[184:185], v[82:83], v[188:189], v[164:165] op_sel:[1,1,0] op_sel_hi:[1,0,1] neg_lo:[1,0,0]
	v_pk_fma_f32 v[186:187], v[82:83], v[188:189], v[184:185] op_sel_hi:[0,1,1]
	v_cvt_pk_bf16_f32 v190, v186, v187
	ds_write_b32 v191, v190 offset:8992
	v_pk_fma_f32 v[184:185], v[82:83], v[186:187], v[166:167] op_sel:[1,1,0] op_sel_hi:[1,0,1] neg_lo:[1,0,0]
	v_pk_fma_f32 v[188:189], v[82:83], v[186:187], v[184:185] op_sel_hi:[0,1,1]
	v_cvt_pk_bf16_f32 v190, v188, v189
	ds_write_b32 v191, v190 offset:8720
	v_pk_fma_f32 v[184:185], v[82:83], v[188:189], v[168:169] op_sel:[1,1,0] op_sel_hi:[1,0,1] neg_lo:[1,0,0]
	v_pk_fma_f32 v[186:187], v[82:83], v[188:189], v[184:185] op_sel_hi:[0,1,1]
	v_mov_b32_e32 v103, v186
	v_mov_b32_e32 v112, v187
	v_cvt_pk_bf16_f32 v190, v186, v187
	ds_write_b32 v191, v190 offset:8448
	s_waitcnt vmcnt(0) lgkmcnt(0)
	ds_read_b128 v[72:75], v81 offset:8448
	ds_read_b128 v[104:107], v81 offset:8512
	s_waitcnt lgkmcnt(1)
	v_mfma_f32_16x16x32_bf16 v[72:75], v[72:75], v[32:35], 0
	s_waitcnt lgkmcnt(0)
	v_mfma_f32_16x16x32_bf16 v[72:75], v[104:107], v[28:31], v[72:75]
	ds_read_b128 v[104:107], v81 offset:8576
	s_waitcnt lgkmcnt(0)
	v_mfma_f32_16x16x32_bf16 v[72:75], v[104:107], v[24:27], v[72:75]
	ds_read_b128 v[104:107], v81 offset:8640
	s_waitcnt lgkmcnt(0)
	v_mfma_f32_16x16x32_bf16 v[72:75], v[104:107], v[20:23], v[72:75]
	v_mfma_f32_16x16x32_bf16 v[104:107], v[76:79], v[40:43], 0
	s_nop 7
	ds_write2_b32 v88, v104, v108 offset1:16
	ds_write2_b32 v88, v105, v109 offset0:132 offset1:148
	ds_write2_b32 v89, v106, v110 offset0:8 offset1:24
	ds_write2_b32 v89, v107, v111 offset0:140 offset1:156
	v_mfma_f32_16x16x32_bf16 v[104:107], v[76:79], v[48:51], 0
	v_mfma_f32_16x16x32_bf16 v[108:111], v[76:79], v[44:47], 0
	s_nop 7
	ds_write2_b32 v88, v104, v108 offset0:32 offset1:48
	ds_write2_b32 v88, v105, v109 offset0:164 offset1:180
	ds_write2_b32 v89, v106, v110 offset0:40 offset1:56
	ds_write2_b32 v89, v107, v111 offset0:172 offset1:188
	v_mfma_f32_16x16x32_bf16 v[104:107], v[76:79], v[56:59], 0
	v_mfma_f32_16x16x32_bf16 v[108:111], v[76:79], v[52:55], 0
	s_nop 7
	ds_write2_b32 v88, v104, v108 offset0:64 offset1:80
	ds_write2_b32 v88, v105, v109 offset0:196 offset1:212
	ds_write2_b32 v89, v106, v110 offset0:72 offset1:88
	ds_write2_b32 v89, v107, v111 offset0:204 offset1:220
	v_mfma_f32_16x16x32_bf16 v[104:107], v[76:79], v[64:67], 0
	v_mfma_f32_16x16x32_bf16 v[76:79], v[76:79], v[60:63], 0
	s_nop 7
	ds_write2_b32 v88, v104, v76 offset0:96 offset1:112
	ds_write2_b32 v88, v105, v77 offset0:228 offset1:244
	ds_write2_b32 v89, v106, v78 offset0:104 offset1:120
	ds_write2_b32 v89, v107, v79 offset0:236 offset1:252
	s_waitcnt vmcnt(0) lgkmcnt(0)
	ds_read2st64_b32 v[76:77], v91 offset0:30 offset1:31
	ds_read2st64_b32 v[140:141], v84 offset0:28 offset1:29
	ds_read2st64_b32 v[142:143], v85 offset0:26 offset1:27
	ds_read2st64_b32 v[144:145], v92 offset0:24 offset1:25
	ds_read2st64_b32 v[146:147], v93 offset0:22 offset1:23
	ds_read2st64_b32 v[148:149], v94 offset0:20 offset1:21
	ds_read2st64_b32 v[150:151], v95 offset0:18 offset1:19
	ds_read2st64_b32 v[152:153], v96 offset0:16 offset1:17
	ds_read2st64_b32 v[154:155], v97 offset0:14 offset1:15
	ds_read2st64_b32 v[156:157], v98 offset0:12 offset1:13
	ds_read2st64_b32 v[158:159], v99 offset0:10 offset1:11
	ds_read2st64_b32 v[160:161], v100 offset0:8 offset1:9
	ds_read2st64_b32 v[162:163], v101 offset0:6 offset1:7
	ds_read2st64_b32 v[164:165], v102 offset0:4 offset1:5
	ds_read2_b32 v[166:167], v87 offset0:132 offset1:196
	ds_read2st64_b32 v[168:169], v87 offset1:1
	v_mov_b32_e32 v186, v103
	v_mov_b32_e32 v187, v112
	v_mfma_f32_16x16x32_bf16 v[40:43], v[68:71], v[40:43], 0
	s_waitcnt lgkmcnt(0)
	v_pk_fma_f32 v[184:185], v[82:83], v[186:187], v[76:77] op_sel:[1,1,0] op_sel_hi:[1,0,1] neg_lo:[1,0,0]
	v_pk_fma_f32 v[188:189], v[82:83], v[186:187], v[184:185] op_sel_hi:[0,1,1]
	v_cvt_pk_bf16_f32 v190, v188, v189
	v_and_b32_e32 v191, 63, v207
	v_lshl_add_u32 v191, v191, 1, v86
	ds_write_b32 v191, v190 offset:12528
	v_pk_fma_f32 v[184:185], v[82:83], v[188:189], v[140:141] op_sel:[1,1,0] op_sel_hi:[1,0,1] neg_lo:[1,0,0]
	v_pk_fma_f32 v[186:187], v[82:83], v[188:189], v[184:185] op_sel_hi:[0,1,1]
	v_cvt_pk_bf16_f32 v190, v186, v187
	ds_write_b32 v191, v190 offset:12256
	v_pk_fma_f32 v[184:185], v[82:83], v[186:187], v[142:143] op_sel:[1,1,0] op_sel_hi:[1,0,1] neg_lo:[1,0,0]
	v_pk_fma_f32 v[188:189], v[82:83], v[186:187], v[184:185] op_sel_hi:[0,1,1]
	v_cvt_pk_bf16_f32 v190, v188, v189
	ds_write_b32 v191, v190 offset:11984
	v_pk_fma_f32 v[184:185], v[82:83], v[188:189], v[144:145] op_sel:[1,1,0] op_sel_hi:[1,0,1] neg_lo:[1,0,0]
	v_pk_fma_f32 v[186:187], v[82:83], v[188:189], v[184:185] op_sel_hi:[0,1,1]
	v_cvt_pk_bf16_f32 v190, v186, v187
	ds_write_b32 v191, v190 offset:11712
	v_pk_fma_f32 v[184:185], v[82:83], v[186:187], v[146:147] op_sel:[1,1,0] op_sel_hi:[1,0,1] neg_lo:[1,0,0]
	v_pk_fma_f32 v[188:189], v[82:83], v[186:187], v[184:185] op_sel_hi:[0,1,1]
	v_cvt_pk_bf16_f32 v190, v188, v189
	ds_write_b32 v191, v190 offset:11440
	v_pk_fma_f32 v[184:185], v[82:83], v[188:189], v[148:149] op_sel:[1,1,0] op_sel_hi:[1,0,1] neg_lo:[1,0,0]
	v_pk_fma_f32 v[186:187], v[82:83], v[188:189], v[184:185] op_sel_hi:[0,1,1]
	v_cvt_pk_bf16_f32 v190, v186, v187
	ds_write_b32 v191, v190 offset:11168
	v_pk_fma_f32 v[184:185], v[82:83], v[186:187], v[150:151] op_sel:[1,1,0] op_sel_hi:[1,0,1] neg_lo:[1,0,0]
	v_pk_fma_f32 v[188:189], v[82:83], v[186:187], v[184:185] op_sel_hi:[0,1,1]
	v_cvt_pk_bf16_f32 v190, v188, v189
	ds_write_b32 v191, v190 offset:10896
	v_pk_fma_f32 v[184:185], v[82:83], v[188:189], v[152:153] op_sel:[1,1,0] op_sel_hi:[1,0,1] neg_lo:[1,0,0]
	v_pk_fma_f32 v[186:187], v[82:83], v[188:189], v[184:185] op_sel_hi:[0,1,1]
	v_cvt_pk_bf16_f32 v190, v186, v187
	ds_write_b32 v191, v190 offset:10624
	v_pk_fma_f32 v[184:185], v[82:83], v[186:187], v[154:155] op_sel:[1,1,0] op_sel_hi:[1,0,1] neg_lo:[1,0,0]
	v_pk_fma_f32 v[188:189], v[82:83], v[186:187], v[184:185] op_sel_hi:[0,1,1]
	v_cvt_pk_bf16_f32 v190, v188, v189
	ds_write_b32 v191, v190 offset:10352
	v_pk_fma_f32 v[184:185], v[82:83], v[188:189], v[156:157] op_sel:[1,1,0] op_sel_hi:[1,0,1] neg_lo:[1,0,0]
	v_pk_fma_f32 v[186:187], v[82:83], v[188:189], v[184:185] op_sel_hi:[0,1,1]
	v_cvt_pk_bf16_f32 v190, v186, v187
	ds_write_b32 v191, v190 offset:10080
	v_pk_fma_f32 v[184:185], v[82:83], v[186:187], v[158:159] op_sel:[1,1,0] op_sel_hi:[1,0,1] neg_lo:[1,0,0]
	v_pk_fma_f32 v[188:189], v[82:83], v[186:187], v[184:185] op_sel_hi:[0,1,1]
	v_cvt_pk_bf16_f32 v190, v188, v189
	ds_write_b32 v191, v190 offset:9808
	v_pk_fma_f32 v[184:185], v[82:83], v[188:189], v[160:161] op_sel:[1,1,0] op_sel_hi:[1,0,1] neg_lo:[1,0,0]
	v_pk_fma_f32 v[186:187], v[82:83], v[188:189], v[184:185] op_sel_hi:[0,1,1]
	v_cvt_pk_bf16_f32 v190, v186, v187
	ds_write_b32 v191, v190 offset:9536
	v_pk_fma_f32 v[184:185], v[82:83], v[186:187], v[162:163] op_sel:[1,1,0] op_sel_hi:[1,0,1] neg_lo:[1,0,0]
	v_pk_fma_f32 v[188:189], v[82:83], v[186:187], v[184:185] op_sel_hi:[0,1,1]
	v_cvt_pk_bf16_f32 v190, v188, v189
	ds_write_b32 v191, v190 offset:9264
	v_pk_fma_f32 v[184:185], v[82:83], v[188:189], v[164:165] op_sel:[1,1,0] op_sel_hi:[1,0,1] neg_lo:[1,0,0]
	v_pk_fma_f32 v[186:187], v[82:83], v[188:189], v[184:185] op_sel_hi:[0,1,1]
	v_cvt_pk_bf16_f32 v190, v186, v187
	ds_write_b32 v191, v190 offset:8992
	v_pk_fma_f32 v[184:185], v[82:83], v[186:187], v[166:167] op_sel:[1,1,0] op_sel_hi:[1,0,1] neg_lo:[1,0,0]
	v_pk_fma_f32 v[188:189], v[82:83], v[186:187], v[184:185] op_sel_hi:[0,1,1]
	v_cvt_pk_bf16_f32 v190, v188, v189
	ds_write_b32 v191, v190 offset:8720
	v_pk_fma_f32 v[184:185], v[82:83], v[188:189], v[168:169] op_sel:[1,1,0] op_sel_hi:[1,0,1] neg_lo:[1,0,0]
	v_pk_fma_f32 v[186:187], v[82:83], v[188:189], v[184:185] op_sel_hi:[0,1,1]
	v_mov_b32_e32 v103, v186
	v_mov_b32_e32 v108, v187
	v_cvt_pk_bf16_f32 v190, v186, v187
	ds_write_b32 v191, v190 offset:8448
	s_waitcnt vmcnt(0) lgkmcnt(0)
	ds_read_b128 v[76:79], v81 offset:8448
	ds_read_b128 v[104:107], v81 offset:8512
	s_waitcnt lgkmcnt(1)
	v_mfma_f32_16x16x32_bf16 v[76:79], v[76:79], v[32:35], 0
	s_waitcnt lgkmcnt(0)
	v_mfma_f32_16x16x32_bf16 v[76:79], v[104:107], v[28:31], v[76:79]
	ds_read_b128 v[104:107], v81 offset:8576
	s_waitcnt lgkmcnt(0)
	v_mfma_f32_16x16x32_bf16 v[76:79], v[104:107], v[24:27], v[76:79]
	ds_read_b128 v[104:107], v81 offset:8640
	ds_write2_b32 v88, v40, v36 offset1:16
	ds_write2_b32 v88, v41, v37 offset0:132 offset1:148
	ds_write2_b32 v89, v42, v38 offset0:8 offset1:24
	ds_write2_b32 v89, v43, v39 offset0:140 offset1:156
	v_mfma_f32_16x16x32_bf16 v[36:39], v[68:71], v[48:51], 0
	v_mfma_f32_16x16x32_bf16 v[40:43], v[68:71], v[44:47], 0
	s_nop 7
	ds_write2_b32 v88, v36, v40 offset0:32 offset1:48
	ds_write2_b32 v88, v37, v41 offset0:164 offset1:180
	ds_write2_b32 v89, v38, v42 offset0:40 offset1:56
	ds_write2_b32 v89, v39, v43 offset0:172 offset1:188
	v_mfma_f32_16x16x32_bf16 v[36:39], v[68:71], v[56:59], 0
	v_mfma_f32_16x16x32_bf16 v[40:43], v[68:71], v[52:55], 0
	s_nop 7
	ds_write2_b32 v88, v36, v40 offset0:64 offset1:80
	ds_write2_b32 v88, v37, v41 offset0:196 offset1:212
	ds_write2_b32 v89, v38, v42 offset0:72 offset1:88
	ds_write2_b32 v89, v39, v43 offset0:204 offset1:220
	v_mfma_f32_16x16x32_bf16 v[36:39], v[68:71], v[64:67], 0
	v_mfma_f32_16x16x32_bf16 v[40:43], v[68:71], v[60:63], 0
	s_nop 7
	ds_write2_b32 v88, v36, v40 offset0:96 offset1:112
	ds_write2_b32 v88, v37, v41 offset0:228 offset1:244
	ds_write2_b32 v89, v38, v42 offset0:104 offset1:120
	ds_write2_b32 v89, v39, v43 offset0:236 offset1:252
	s_waitcnt vmcnt(0) lgkmcnt(0)
	ds_read2st64_b32 v[36:37], v91 offset0:30 offset1:31
	ds_read2st64_b32 v[140:141], v84 offset0:28 offset1:29
	ds_read2st64_b32 v[142:143], v85 offset0:26 offset1:27
	ds_read2st64_b32 v[144:145], v92 offset0:24 offset1:25
	ds_read2st64_b32 v[146:147], v93 offset0:22 offset1:23
	ds_read2st64_b32 v[148:149], v94 offset0:20 offset1:21
	ds_read2st64_b32 v[150:151], v95 offset0:18 offset1:19
	ds_read2st64_b32 v[152:153], v96 offset0:16 offset1:17
	ds_read2st64_b32 v[154:155], v97 offset0:14 offset1:15
	ds_read2st64_b32 v[156:157], v98 offset0:12 offset1:13
	ds_read2st64_b32 v[158:159], v99 offset0:10 offset1:11
	ds_read2st64_b32 v[160:161], v100 offset0:8 offset1:9
	ds_read2st64_b32 v[162:163], v101 offset0:6 offset1:7
	ds_read2st64_b32 v[164:165], v102 offset0:4 offset1:5
	ds_read2_b32 v[166:167], v87 offset0:132 offset1:196
	ds_read2st64_b32 v[168:169], v87 offset1:1
	v_mov_b32_e32 v186, v103
	v_mov_b32_e32 v187, v108
	s_waitcnt lgkmcnt(0)
	v_mfma_f32_16x16x32_bf16 v[76:79], v[104:107], v[20:23], v[76:79]
	v_pk_fma_f32 v[184:185], v[82:83], v[186:187], v[36:37] op_sel:[1,1,0] op_sel_hi:[1,0,1] neg_lo:[1,0,0]
	v_pk_fma_f32 v[188:189], v[82:83], v[186:187], v[184:185] op_sel_hi:[0,1,1]
	v_cvt_pk_bf16_f32 v190, v188, v189
	v_and_b32_e32 v191, 63, v207
	v_lshl_add_u32 v191, v191, 1, v86
	ds_write_b32 v191, v190 offset:12528
	v_pk_fma_f32 v[184:185], v[82:83], v[188:189], v[140:141] op_sel:[1,1,0] op_sel_hi:[1,0,1] neg_lo:[1,0,0]
	v_pk_fma_f32 v[186:187], v[82:83], v[188:189], v[184:185] op_sel_hi:[0,1,1]
	v_cvt_pk_bf16_f32 v190, v186, v187
	ds_write_b32 v191, v190 offset:12256
	v_pk_fma_f32 v[184:185], v[82:83], v[186:187], v[142:143] op_sel:[1,1,0] op_sel_hi:[1,0,1] neg_lo:[1,0,0]
	v_pk_fma_f32 v[188:189], v[82:83], v[186:187], v[184:185] op_sel_hi:[0,1,1]
	v_cvt_pk_bf16_f32 v190, v188, v189
	ds_write_b32 v191, v190 offset:11984
	v_pk_fma_f32 v[184:185], v[82:83], v[188:189], v[144:145] op_sel:[1,1,0] op_sel_hi:[1,0,1] neg_lo:[1,0,0]
	v_pk_fma_f32 v[186:187], v[82:83], v[188:189], v[184:185] op_sel_hi:[0,1,1]
	v_cvt_pk_bf16_f32 v190, v186, v187
	ds_write_b32 v191, v190 offset:11712
	v_pk_fma_f32 v[184:185], v[82:83], v[186:187], v[146:147] op_sel:[1,1,0] op_sel_hi:[1,0,1] neg_lo:[1,0,0]
	v_pk_fma_f32 v[188:189], v[82:83], v[186:187], v[184:185] op_sel_hi:[0,1,1]
	v_cvt_pk_bf16_f32 v190, v188, v189
	ds_write_b32 v191, v190 offset:11440
	v_pk_fma_f32 v[184:185], v[82:83], v[188:189], v[148:149] op_sel:[1,1,0] op_sel_hi:[1,0,1] neg_lo:[1,0,0]
	v_pk_fma_f32 v[186:187], v[82:83], v[188:189], v[184:185] op_sel_hi:[0,1,1]
	v_cvt_pk_bf16_f32 v190, v186, v187
	ds_write_b32 v191, v190 offset:11168
	v_pk_fma_f32 v[184:185], v[82:83], v[186:187], v[150:151] op_sel:[1,1,0] op_sel_hi:[1,0,1] neg_lo:[1,0,0]
	v_pk_fma_f32 v[188:189], v[82:83], v[186:187], v[184:185] op_sel_hi:[0,1,1]
	v_cvt_pk_bf16_f32 v190, v188, v189
	ds_write_b32 v191, v190 offset:10896
	v_pk_fma_f32 v[184:185], v[82:83], v[188:189], v[152:153] op_sel:[1,1,0] op_sel_hi:[1,0,1] neg_lo:[1,0,0]
	v_pk_fma_f32 v[186:187], v[82:83], v[188:189], v[184:185] op_sel_hi:[0,1,1]
	v_cvt_pk_bf16_f32 v190, v186, v187
	ds_write_b32 v191, v190 offset:10624
	v_pk_fma_f32 v[184:185], v[82:83], v[186:187], v[154:155] op_sel:[1,1,0] op_sel_hi:[1,0,1] neg_lo:[1,0,0]
	v_pk_fma_f32 v[188:189], v[82:83], v[186:187], v[184:185] op_sel_hi:[0,1,1]
	v_cvt_pk_bf16_f32 v190, v188, v189
	ds_write_b32 v191, v190 offset:10352
	v_pk_fma_f32 v[184:185], v[82:83], v[188:189], v[156:157] op_sel:[1,1,0] op_sel_hi:[1,0,1] neg_lo:[1,0,0]
	v_pk_fma_f32 v[186:187], v[82:83], v[188:189], v[184:185] op_sel_hi:[0,1,1]
	v_cvt_pk_bf16_f32 v190, v186, v187
	ds_write_b32 v191, v190 offset:10080
	v_pk_fma_f32 v[184:185], v[82:83], v[186:187], v[158:159] op_sel:[1,1,0] op_sel_hi:[1,0,1] neg_lo:[1,0,0]
	v_pk_fma_f32 v[188:189], v[82:83], v[186:187], v[184:185] op_sel_hi:[0,1,1]
	v_cvt_pk_bf16_f32 v190, v188, v189
	ds_write_b32 v191, v190 offset:9808
	v_pk_fma_f32 v[184:185], v[82:83], v[188:189], v[160:161] op_sel:[1,1,0] op_sel_hi:[1,0,1] neg_lo:[1,0,0]
	v_pk_fma_f32 v[186:187], v[82:83], v[188:189], v[184:185] op_sel_hi:[0,1,1]
	v_cvt_pk_bf16_f32 v190, v186, v187
	ds_write_b32 v191, v190 offset:9536
	v_pk_fma_f32 v[184:185], v[82:83], v[186:187], v[162:163] op_sel:[1,1,0] op_sel_hi:[1,0,1] neg_lo:[1,0,0]
	v_pk_fma_f32 v[188:189], v[82:83], v[186:187], v[184:185] op_sel_hi:[0,1,1]
	v_cvt_pk_bf16_f32 v190, v188, v189
	ds_write_b32 v191, v190 offset:9264
	v_pk_fma_f32 v[184:185], v[82:83], v[188:189], v[164:165] op_sel:[1,1,0] op_sel_hi:[1,0,1] neg_lo:[1,0,0]
	v_pk_fma_f32 v[186:187], v[82:83], v[188:189], v[184:185] op_sel_hi:[0,1,1]
	v_cvt_pk_bf16_f32 v190, v186, v187
	ds_write_b32 v191, v190 offset:8992
	v_pk_fma_f32 v[184:185], v[82:83], v[186:187], v[166:167] op_sel:[1,1,0] op_sel_hi:[1,0,1] neg_lo:[1,0,0]
	v_pk_fma_f32 v[188:189], v[82:83], v[186:187], v[184:185] op_sel_hi:[0,1,1]
	v_cvt_pk_bf16_f32 v190, v188, v189
	ds_write_b32 v191, v190 offset:8720
	v_pk_fma_f32 v[184:185], v[82:83], v[188:189], v[168:169] op_sel:[1,1,0] op_sel_hi:[1,0,1] neg_lo:[1,0,0]
	v_pk_fma_f32 v[186:187], v[82:83], v[188:189], v[184:185] op_sel_hi:[0,1,1]
	v_mov_b32_e32 v36, v186
	v_mov_b32_e32 v37, v187
	v_cvt_pk_bf16_f32 v190, v186, v187
	ds_write_b32 v191, v190 offset:8448
	s_waitcnt vmcnt(0) lgkmcnt(0)
	ds_read_b128 v[36:39], v81 offset:8448
	s_waitcnt lgkmcnt(0)
	v_mfma_f32_16x16x32_bf16 v[32:35], v[36:39], v[32:35], 0
	ds_read_b128 v[36:39], v81 offset:8512
	s_waitcnt lgkmcnt(0)
	v_mfma_f32_16x16x32_bf16 v[28:31], v[36:39], v[28:31], v[32:35]
	s_nop 4
	ds_read_b128 v[32:35], v81 offset:8576
	s_waitcnt lgkmcnt(0)
	v_mfma_f32_16x16x32_bf16 v[24:27], v[32:35], v[24:27], v[28:31]
	s_nop 2
	ds_read_b128 v[28:31], v81 offset:8640
	s_waitcnt lgkmcnt(0)
	v_mfma_f32_16x16x32_bf16 v[20:23], v[28:31], v[20:23], v[24:27]
	s_nop 7
	v_pk_add_f32 v[24:25], v[0:1], v[20:21]
	v_and_or_b32 v0, v90, 15, v80
	v_add_u32_e32 v20, s6, v0
	v_ashrrev_i32_e32 v21, 31, v20
	v_lshrrev_b32_e32 v1, 2, v90
	v_lshl_add_u64 v[20:21], v[20:21], 2, s[76:77]
	v_and_b32_e32 v1, 12, v1
	global_load_dword v28, v[20:21], off
	v_add_u32_e32 v20, s8, v1
	v_ashrrev_i32_e32 v21, 31, v20
	v_ashrrev_i32_e32 v1, 31, v0
	v_lshlrev_b64 v[26:27], 9, v[20:21]
	v_lshl_add_u64 v[26:27], v[26:27], 0, v[0:1]
	v_lshl_add_u64 v[30:31], v[26:27], 1, s[36:37]
	global_load_ushort v29, v[30:31], off
	global_load_ushort v141, v[30:31], off offset:1024
	global_load_ushort v142, v[30:31], off offset:2048
	global_load_ushort v143, v[30:31], off offset:3072
	s_mov_b64 s[0:1], 0x4000
	v_lshl_add_u64 v[156:157], v[30:31], 0, s[0:1]
	global_load_ushort v144, v[156:157], off
	global_load_ushort v145, v[156:157], off offset:1024
	global_load_ushort v146, v[156:157], off offset:2048
	global_load_ushort v147, v[156:157], off offset:3072
	s_mov_b64 s[0:1], 0x8000
	v_lshl_add_u64 v[158:159], v[30:31], 0, s[0:1]
	global_load_ushort v148, v[158:159], off
	global_load_ushort v149, v[158:159], off offset:1024
	global_load_ushort v150, v[158:159], off offset:2048
	global_load_ushort v151, v[158:159], off offset:3072
	s_mov_b64 s[0:1], 0xc000
	v_lshl_add_u64 v[160:161], v[30:31], 0, s[0:1]
	global_load_ushort v152, v[160:161], off
	global_load_ushort v153, v[160:161], off offset:1024
	global_load_ushort v154, v[160:161], off offset:2048
	global_load_ushort v155, v[160:161], off offset:3072
	s_waitcnt vmcnt(0) lgkmcnt(0)
	v_lshlrev_b32_e32 v29, 16, v29
	v_fma_f32 v24, v28, v29, v24
	v_mul_f32_e32 v29, 0x3d372713, v24
	v_mul_f32_e32 v29, v24, v29
	v_fma_f32 v29, v24, v29, v24
	v_mul_f32_e32 v29, 0x3f4c422a, v29
	v_mul_f32_e32 v30, 0x4038aa3b, v29
	v_exp_f32_e32 v30, v30
	s_nop 0
	v_add_f32_e32 v30, 1.0, v30
	v_rcp_f32_e32 v30, v30
	s_nop 0
	v_fma_f32 v29, v30, -2.0, 1.0
	v_mul_f32_e32 v24, 0.5, v24
	v_add_f32_e32 v29, 1.0, v29
	v_mul_f32_e32 v24, v24, v29
	v_cvt_pk_bf16_f32 v24, v24, s0
	v_lshl_add_u64 v[26:27], v[26:27], 1, s[44:45]
	global_store_short v[26:27], v24, off
	v_lshlrev_b64 v[26:27], 9, v[20:21]
	v_lshl_add_u64 v[26:27], v[26:27], 0, v[0:1]
	s_mov_b64 s[0:1], 0x200
	v_lshl_add_u64 v[26:27], v[26:27], 0, s[0:1]
	v_lshl_add_u64 v[30:31], v[26:27], 1, s[36:37]
	v_mov_b32_e32 v24, v141
	v_pk_add_f32 v[2:3], v[2:3], 0 op_sel_hi:[1,0]
	s_nop 0
	v_pk_add_f32 v[2:3], v[2:3], v[22:23]
	v_lshlrev_b32_e32 v22, 16, v24
	v_fmac_f32_e32 v25, v28, v22
	v_mul_f32_e32 v22, 0x3d372713, v25
	v_mul_f32_e32 v22, v25, v22
	v_fma_f32 v22, v25, v22, v25
	v_mul_f32_e32 v22, 0x3f4c422a, v22
	v_mul_f32_e32 v23, 0x4038aa3b, v22
	v_exp_f32_e32 v23, v23
	s_nop 0
	v_add_f32_e32 v23, 1.0, v23
	v_rcp_f32_e32 v23, v23
	s_nop 0
	v_fma_f32 v22, v23, -2.0, 1.0
	v_mul_f32_e32 v24, 0.5, v25
	v_add_f32_e32 v22, 1.0, v22
	v_mul_f32_e32 v22, v24, v22
	v_cvt_pk_bf16_f32 v24, v22, s0
	v_lshl_add_u64 v[22:23], v[26:27], 1, s[44:45]
	global_store_short v[22:23], v24, off
	v_lshlrev_b64 v[22:23], 9, v[20:21]
	v_lshl_add_u64 v[22:23], v[22:23], 0, v[0:1]
	s_mov_b64 s[0:1], 0x400
	v_lshl_add_u64 v[22:23], v[22:23], 0, s[0:1]
	v_lshl_add_u64 v[24:25], v[22:23], 1, s[36:37]
	v_mov_b32_e32 v24, v142
	v_lshlrev_b32_e32 v24, 16, v24
	v_fma_f32 v2, v28, v24, v2
	v_mul_f32_e32 v24, 0x3d372713, v2
	v_mul_f32_e32 v24, v2, v24
	v_fma_f32 v24, v2, v24, v2
	v_mul_f32_e32 v24, 0x3f4c422a, v24
	v_mul_f32_e32 v25, 0x4038aa3b, v24
	v_exp_f32_e32 v25, v25
	s_nop 0
	v_add_f32_e32 v25, 1.0, v25
	v_rcp_f32_e32 v25, v25
	s_nop 0
	v_fma_f32 v24, v25, -2.0, 1.0
	v_mul_f32_e32 v2, 0.5, v2
	v_add_f32_e32 v24, 1.0, v24
	v_mul_f32_e32 v2, v2, v24
	v_cvt_pk_bf16_f32 v2, v2, s0
	v_lshl_add_u64 v[22:23], v[22:23], 1, s[44:45]
	global_store_short v[22:23], v2, off
	v_lshlrev_b64 v[22:23], 9, v[20:21]
	v_lshl_add_u64 v[22:23], v[22:23], 0, v[0:1]
	s_mov_b64 s[0:1], 0x600
	v_lshl_add_u64 v[22:23], v[22:23], 0, s[0:1]
	v_lshl_add_u64 v[24:25], v[22:23], 1, s[36:37]
	v_mov_b32_e32 v2, v143
	v_lshlrev_b32_e32 v2, 16, v2
	v_fmac_f32_e32 v3, v28, v2
	v_mul_f32_e32 v2, 0x3d372713, v3
	v_mul_f32_e32 v2, v3, v2
	v_fma_f32 v2, v3, v2, v3
	v_mul_f32_e32 v2, 0x3f4c422a, v2
	v_mul_f32_e32 v24, 0x4038aa3b, v2
	v_exp_f32_e32 v24, v24
	s_nop 0
	v_add_f32_e32 v24, 1.0, v24
	v_rcp_f32_e32 v24, v24
	s_nop 0
	v_fma_f32 v2, v24, -2.0, 1.0
	v_mul_f32_e32 v3, 0.5, v3
	v_add_f32_e32 v2, 1.0, v2
	v_mul_f32_e32 v2, v3, v2
	v_cvt_pk_bf16_f32 v24, v2, s0
	v_lshl_add_u64 v[2:3], v[22:23], 1, s[44:45]
	global_store_short v[2:3], v24, off
	v_lshlrev_b64 v[2:3], 9, v[20:21]
	v_lshl_add_u64 v[2:3], v[2:3], 0, v[0:1]
	s_mov_b64 s[0:1], 0x2000
	v_lshl_add_u64 v[2:3], v[2:3], 0, s[0:1]
	v_lshl_add_u64 v[22:23], v[2:3], 1, s[36:37]
	v_mov_b32_e32 v22, v144
	v_pk_add_f32 v[4:5], v[4:5], 0 op_sel_hi:[1,0]
	v_lshlrev_b32_e32 v22, 16, v22
	v_pk_add_f32 v[4:5], v[4:5], v[76:77]
	s_nop 0
	v_fma_f32 v4, v28, v22, v4
	v_mul_f32_e32 v22, 0x3d372713, v4
	v_mul_f32_e32 v22, v4, v22
	v_fma_f32 v22, v4, v22, v4
	v_mul_f32_e32 v22, 0x3f4c422a, v22
	v_mul_f32_e32 v23, 0x4038aa3b, v22
	v_exp_f32_e32 v23, v23
	s_nop 0
	v_add_f32_e32 v23, 1.0, v23
	v_rcp_f32_e32 v23, v23
	s_nop 0
	v_fma_f32 v22, v23, -2.0, 1.0
	v_mul_f32_e32 v4, 0.5, v4
	v_add_f32_e32 v22, 1.0, v22
	v_mul_f32_e32 v4, v4, v22
	v_cvt_pk_bf16_f32 v4, v4, s0
	v_lshl_add_u64 v[2:3], v[2:3], 1, s[44:45]
	global_store_short v[2:3], v4, off
	v_lshlrev_b64 v[2:3], 9, v[20:21]
	v_lshl_add_u64 v[2:3], v[2:3], 0, v[0:1]
	s_mov_b64 s[0:1], 0x2200
	v_lshl_add_u64 v[22:23], v[2:3], 0, s[0:1]
	v_lshl_add_u64 v[2:3], v[22:23], 1, s[36:37]
	v_mov_b32_e32 v4, v145
	v_pk_add_f32 v[2:3], v[6:7], 0 op_sel_hi:[1,0]
	v_lshlrev_b32_e32 v4, 16, v4
	v_fmac_f32_e32 v5, v28, v4
	v_mul_f32_e32 v4, 0x3d372713, v5
	v_mul_f32_e32 v4, v5, v4
	v_fma_f32 v4, v5, v4, v5
	v_mul_f32_e32 v4, 0x3f4c422a, v4
	v_pk_add_f32 v[2:3], v[2:3], v[78:79]
	v_mul_f32_e32 v6, 0x4038aa3b, v4
	v_exp_f32_e32 v6, v6
	s_nop 0
	v_add_f32_e32 v6, 1.0, v6
	v_rcp_f32_e32 v6, v6
	s_nop 0
	v_fma_f32 v4, v6, -2.0, 1.0
	v_mul_f32_e32 v5, 0.5, v5
	v_add_f32_e32 v4, 1.0, v4
	v_mul_f32_e32 v4, v5, v4
	v_cvt_pk_bf16_f32 v6, v4, s0
	v_lshl_add_u64 v[4:5], v[22:23], 1, s[44:45]
	global_store_short v[4:5], v6, off
	v_lshlrev_b64 v[4:5], 9, v[20:21]
	v_lshl_add_u64 v[4:5], v[4:5], 0, v[0:1]
	s_mov_b64 s[0:1], 0x2400
	v_lshl_add_u64 v[4:5], v[4:5], 0, s[0:1]
	v_lshl_add_u64 v[6:7], v[4:5], 1, s[36:37]
	v_mov_b32_e32 v6, v146
	v_lshlrev_b32_e32 v6, 16, v6
	v_fma_f32 v2, v28, v6, v2
	v_mul_f32_e32 v6, 0x3d372713, v2
	v_mul_f32_e32 v6, v2, v6
	v_fma_f32 v6, v2, v6, v2
	v_mul_f32_e32 v6, 0x3f4c422a, v6
	v_mul_f32_e32 v7, 0x4038aa3b, v6
	v_exp_f32_e32 v7, v7
	s_nop 0
	v_add_f32_e32 v7, 1.0, v7
	v_rcp_f32_e32 v7, v7
	s_nop 0
	v_fma_f32 v6, v7, -2.0, 1.0
	v_mul_f32_e32 v2, 0.5, v2
	v_add_f32_e32 v6, 1.0, v6
	v_mul_f32_e32 v2, v2, v6
	v_cvt_pk_bf16_f32 v2, v2, s0
	v_lshl_add_u64 v[4:5], v[4:5], 1, s[44:45]
	global_store_short v[4:5], v2, off
	v_lshlrev_b64 v[4:5], 9, v[20:21]
	v_lshl_add_u64 v[4:5], v[4:5], 0, v[0:1]
	s_mov_b64 s[0:1], 0x2600
	v_lshl_add_u64 v[4:5], v[4:5], 0, s[0:1]
	v_lshl_add_u64 v[6:7], v[4:5], 1, s[36:37]
	v_mov_b32_e32 v2, v147
	v_lshlrev_b32_e32 v2, 16, v2
	v_fmac_f32_e32 v3, v28, v2
	v_mul_f32_e32 v2, 0x3d372713, v3
	v_mul_f32_e32 v2, v3, v2
	v_fma_f32 v2, v3, v2, v3
	v_mul_f32_e32 v2, 0x3f4c422a, v2
	v_mul_f32_e32 v6, 0x4038aa3b, v2
	v_exp_f32_e32 v6, v6
	s_nop 0
	v_add_f32_e32 v6, 1.0, v6
	v_rcp_f32_e32 v6, v6
	s_nop 0
	v_fma_f32 v2, v6, -2.0, 1.0
	v_mul_f32_e32 v3, 0.5, v3
	v_add_f32_e32 v2, 1.0, v2
	v_mul_f32_e32 v2, v3, v2
	v_cvt_pk_bf16_f32 v6, v2, s0
	v_lshl_add_u64 v[2:3], v[4:5], 1, s[44:45]
	global_store_short v[2:3], v6, off
	v_lshlrev_b64 v[2:3], 9, v[20:21]
	v_lshl_add_u64 v[2:3], v[2:3], 0, v[0:1]
	s_mov_b64 s[0:1], 0x4000
	v_lshl_add_u64 v[2:3], v[2:3], 0, s[0:1]
	v_lshl_add_u64 v[4:5], v[2:3], 1, s[36:37]
	v_mov_b32_e32 v6, v148
	v_pk_add_f32 v[4:5], v[8:9], 0 op_sel_hi:[1,0]
	v_lshlrev_b32_e32 v6, 16, v6
	v_pk_add_f32 v[4:5], v[4:5], v[72:73]
	s_nop 0
	v_fma_f32 v4, v28, v6, v4
	v_mul_f32_e32 v6, 0x3d372713, v4
	v_mul_f32_e32 v6, v4, v6
	v_fma_f32 v6, v4, v6, v4
	v_mul_f32_e32 v6, 0x3f4c422a, v6
	v_mul_f32_e32 v7, 0x4038aa3b, v6
	v_exp_f32_e32 v7, v7
	s_nop 0
	v_add_f32_e32 v7, 1.0, v7
	v_rcp_f32_e32 v7, v7
	s_nop 0
	v_fma_f32 v6, v7, -2.0, 1.0
	v_mul_f32_e32 v4, 0.5, v4
	v_add_f32_e32 v6, 1.0, v6
	v_mul_f32_e32 v4, v4, v6
	v_cvt_pk_bf16_f32 v4, v4, s0
	v_lshl_add_u64 v[2:3], v[2:3], 1, s[44:45]
	global_store_short v[2:3], v4, off
	v_lshlrev_b64 v[2:3], 9, v[20:21]
	v_lshl_add_u64 v[2:3], v[2:3], 0, v[0:1]
	s_mov_b64 s[0:1], 0x4200
	v_lshl_add_u64 v[6:7], v[2:3], 0, s[0:1]
	v_lshl_add_u64 v[2:3], v[6:7], 1, s[36:37]
	v_mov_b32_e32 v4, v149
	v_pk_add_f32 v[2:3], v[10:11], 0 op_sel_hi:[1,0]
	v_lshlrev_b32_e32 v4, 16, v4
	v_fmac_f32_e32 v5, v28, v4
	v_mul_f32_e32 v4, 0x3d372713, v5
	v_mul_f32_e32 v4, v5, v4
	v_fma_f32 v4, v5, v4, v5
	v_mul_f32_e32 v4, 0x3f4c422a, v4
	v_pk_add_f32 v[2:3], v[2:3], v[74:75]
	v_mul_f32_e32 v8, 0x4038aa3b, v4
	v_exp_f32_e32 v8, v8
	s_nop 0
	v_add_f32_e32 v8, 1.0, v8
	v_rcp_f32_e32 v8, v8
	s_nop 0
	v_fma_f32 v4, v8, -2.0, 1.0
	v_mul_f32_e32 v5, 0.5, v5
	v_add_f32_e32 v4, 1.0, v4
	v_mul_f32_e32 v4, v5, v4
	v_cvt_pk_bf16_f32 v8, v4, s0
	v_lshl_add_u64 v[4:5], v[6:7], 1, s[44:45]
	global_store_short v[4:5], v8, off
	v_lshlrev_b64 v[4:5], 9, v[20:21]
	v_lshl_add_u64 v[4:5], v[4:5], 0, v[0:1]
	s_mov_b64 s[0:1], 0x4400
	v_lshl_add_u64 v[4:5], v[4:5], 0, s[0:1]
	v_lshl_add_u64 v[6:7], v[4:5], 1, s[36:37]
	v_mov_b32_e32 v6, v150
	v_lshlrev_b32_e32 v6, 16, v6
	v_fma_f32 v2, v28, v6, v2
	v_mul_f32_e32 v6, 0x3d372713, v2
	v_mul_f32_e32 v6, v2, v6
	v_fma_f32 v6, v2, v6, v2
	v_mul_f32_e32 v6, 0x3f4c422a, v6
	v_mul_f32_e32 v7, 0x4038aa3b, v6
	v_exp_f32_e32 v7, v7
	s_nop 0
	v_add_f32_e32 v7, 1.0, v7
	v_rcp_f32_e32 v7, v7
	s_nop 0
	v_fma_f32 v6, v7, -2.0, 1.0
	v_mul_f32_e32 v2, 0.5, v2
	v_add_f32_e32 v6, 1.0, v6
	v_mul_f32_e32 v2, v2, v6
	v_cvt_pk_bf16_f32 v2, v2, s0
	v_lshl_add_u64 v[4:5], v[4:5], 1, s[44:45]
	global_store_short v[4:5], v2, off
	v_lshlrev_b64 v[4:5], 9, v[20:21]
	v_lshl_add_u64 v[4:5], v[4:5], 0, v[0:1]
	s_mov_b64 s[0:1], 0x4600
	v_lshl_add_u64 v[4:5], v[4:5], 0, s[0:1]
	v_lshl_add_u64 v[6:7], v[4:5], 1, s[36:37]
	v_mov_b32_e32 v2, v151
	v_lshlrev_b32_e32 v2, 16, v2
	v_fmac_f32_e32 v3, v28, v2
	v_mul_f32_e32 v2, 0x3d372713, v3
	v_mul_f32_e32 v2, v3, v2
	v_fma_f32 v2, v3, v2, v3
	v_mul_f32_e32 v2, 0x3f4c422a, v2
	v_mul_f32_e32 v6, 0x4038aa3b, v2
	v_exp_f32_e32 v6, v6
	s_nop 0
	v_add_f32_e32 v6, 1.0, v6
	v_rcp_f32_e32 v6, v6
	s_nop 0
	v_fma_f32 v2, v6, -2.0, 1.0
	v_mul_f32_e32 v3, 0.5, v3
	v_add_f32_e32 v2, 1.0, v2
	v_mul_f32_e32 v2, v3, v2
	v_cvt_pk_bf16_f32 v6, v2, s0
	v_lshl_add_u64 v[2:3], v[4:5], 1, s[44:45]
	global_store_short v[2:3], v6, off
	v_lshlrev_b64 v[2:3], 9, v[20:21]
	v_lshl_add_u64 v[2:3], v[2:3], 0, v[0:1]
	s_mov_b64 s[0:1], 0x6000
	v_lshl_add_u64 v[2:3], v[2:3], 0, s[0:1]
	v_lshl_add_u64 v[4:5], v[2:3], 1, s[36:37]
	v_mov_b32_e32 v6, v152
	v_pk_add_f32 v[4:5], v[12:13], 0 op_sel_hi:[1,0]
	v_lshlrev_b32_e32 v6, 16, v6
	v_pk_add_f32 v[4:5], v[4:5], v[16:17]
	s_nop 0
	v_fma_f32 v4, v28, v6, v4
	v_mul_f32_e32 v6, 0x3d372713, v4
	v_mul_f32_e32 v6, v4, v6
	v_fma_f32 v6, v4, v6, v4
	v_mul_f32_e32 v6, 0x3f4c422a, v6
	v_mul_f32_e32 v7, 0x4038aa3b, v6
	v_exp_f32_e32 v7, v7
	s_nop 0
	v_add_f32_e32 v7, 1.0, v7
	v_rcp_f32_e32 v7, v7
	s_nop 0
	v_fma_f32 v6, v7, -2.0, 1.0
	v_mul_f32_e32 v4, 0.5, v4
	v_add_f32_e32 v6, 1.0, v6
	v_mul_f32_e32 v4, v4, v6
	v_cvt_pk_bf16_f32 v4, v4, s0
	v_lshl_add_u64 v[2:3], v[2:3], 1, s[44:45]
	global_store_short v[2:3], v4, off
	v_lshlrev_b64 v[2:3], 9, v[20:21]
	v_lshl_add_u64 v[2:3], v[2:3], 0, v[0:1]
	s_mov_b64 s[0:1], 0x6200
	v_lshl_add_u64 v[6:7], v[2:3], 0, s[0:1]
	v_lshl_add_u64 v[2:3], v[6:7], 1, s[36:37]
	v_mov_b32_e32 v4, v153
	v_pk_add_f32 v[2:3], v[14:15], 0 op_sel_hi:[1,0]
	v_lshlrev_b32_e32 v4, 16, v4
	v_fmac_f32_e32 v5, v28, v4
	v_mul_f32_e32 v4, 0x3d372713, v5
	v_mul_f32_e32 v4, v5, v4
	v_fma_f32 v4, v5, v4, v5
	v_mul_f32_e32 v4, 0x3f4c422a, v4
	v_pk_add_f32 v[2:3], v[2:3], v[18:19]
	v_mul_f32_e32 v8, 0x4038aa3b, v4
	v_exp_f32_e32 v8, v8
	s_nop 0
	v_add_f32_e32 v8, 1.0, v8
	v_rcp_f32_e32 v8, v8
	s_nop 0
	v_fma_f32 v4, v8, -2.0, 1.0
	v_mul_f32_e32 v5, 0.5, v5
	v_add_f32_e32 v4, 1.0, v4
	v_mul_f32_e32 v4, v5, v4
	v_cvt_pk_bf16_f32 v8, v4, s0
	v_lshl_add_u64 v[4:5], v[6:7], 1, s[44:45]
	global_store_short v[4:5], v8, off
	v_lshlrev_b64 v[4:5], 9, v[20:21]
	v_lshl_add_u64 v[4:5], v[4:5], 0, v[0:1]
	s_mov_b64 s[0:1], 0x6400
	v_lshl_add_u64 v[4:5], v[4:5], 0, s[0:1]
	v_lshl_add_u64 v[6:7], v[4:5], 1, s[36:37]
	v_mov_b32_e32 v6, v154
	v_lshlrev_b32_e32 v6, 16, v6
	v_fma_f32 v2, v28, v6, v2
	v_mul_f32_e32 v6, 0x3d372713, v2
	v_mul_f32_e32 v6, v2, v6
	v_fma_f32 v6, v2, v6, v2
	v_mul_f32_e32 v6, 0x3f4c422a, v6
	v_mul_f32_e32 v7, 0x4038aa3b, v6
	v_exp_f32_e32 v7, v7
	s_nop 0
	v_add_f32_e32 v7, 1.0, v7
	v_rcp_f32_e32 v7, v7
	s_nop 0
	v_fma_f32 v6, v7, -2.0, 1.0
	v_mul_f32_e32 v2, 0.5, v2
	v_add_f32_e32 v6, 1.0, v6
	v_mul_f32_e32 v2, v2, v6
	v_cvt_pk_bf16_f32 v2, v2, s0
	v_lshl_add_u64 v[4:5], v[4:5], 1, s[44:45]
	global_store_short v[4:5], v2, off
	v_lshlrev_b64 v[4:5], 9, v[20:21]
	v_lshl_add_u64 v[0:1], v[4:5], 0, v[0:1]
	s_mov_b64 s[0:1], 0x6600
	v_lshl_add_u64 v[0:1], v[0:1], 0, s[0:1]
	v_lshl_add_u64 v[4:5], v[0:1], 1, s[36:37]
	v_mov_b32_e32 v2, v155
	v_lshlrev_b32_e32 v2, 16, v2
	v_fmac_f32_e32 v3, v28, v2
	v_mul_f32_e32 v2, 0x3d372713, v3
	v_mul_f32_e32 v2, v3, v2
	v_fma_f32 v2, v3, v2, v3
	v_mul_f32_e32 v2, 0x3f4c422a, v2
	v_mul_f32_e32 v4, 0x4038aa3b, v2
	v_exp_f32_e32 v4, v4
	s_nop 0
	v_add_f32_e32 v4, 1.0, v4
	v_rcp_f32_e32 v4, v4
	s_nop 0
	v_fma_f32 v2, v4, -2.0, 1.0
	v_mul_f32_e32 v3, 0.5, v3
	v_add_f32_e32 v2, 1.0, v2
	v_mul_f32_e32 v2, v3, v2
	v_cvt_pk_bf16_f32 v2, v2, s0
	v_lshl_add_u64 v[0:1], v[0:1], 1, s[44:45]
	global_store_short v[0:1], v2, off
	s_mov_b64 s[0:1], 0
